# v18 + fused LDS-store-ladder / next-k-tile global loads in FFN_DOWN, OPROJ, QKV, MLA_DOWN, MLA_UP k-loops
# baseline (speedup 1.0000x reference)
.LBB0_479:
	s_and_saveexec_b64 s[48:49], vcc
	s_xor_b64 s[48:49], exec, s[48:49]
	s_cbranch_execz .LBB0_484
	s_cmp_gt_u32 s65, 13
	s_cbranch_scc1 .Lfl_OPROJ_0_old
	s_andn2_b32 s50, 0x10000, s72
	v_add_u32_e32 v0, s50, v198
	s_waitcnt vmcnt(7)
	ds_write_b128 v0, v[144:147]
	v_lshl_add_u64 v[2:3], v[190:191], 0, s[20:21]
	global_load_dwordx4 v[144:147], v[2:3], off
	s_waitcnt vmcnt(4)
	ds_write_b128 v0, v[152:155] offset:32768
	v_lshl_add_u64 v[2:3], v[182:183], 0, s[20:21]
	global_load_dwordx4 v[152:155], v[2:3], off
	s_waitcnt vmcnt(5)
	ds_write_b128 v0, v[148:151] offset:8192
	v_lshl_add_u64 v[2:3], v[188:189], 0, s[20:21]
	global_load_dwordx4 v[148:151], v[2:3], off
	s_waitcnt vmcnt(5)
	ds_write_b128 v0, v[160:163] offset:40960
	v_lshl_add_u64 v[2:3], v[180:181], 0, s[20:21]
	global_load_dwordx4 v[160:163], v[2:3], off
	s_waitcnt vmcnt(6)
	ds_write_b128 v0, v[156:159] offset:16384
	v_lshl_add_u64 v[2:3], v[186:187], 0, s[20:21]
	global_load_dwordx4 v[156:159], v[2:3], off
	s_waitcnt vmcnt(6)
	ds_write_b128 v0, v[164:167] offset:49152
	v_lshl_add_u64 v[2:3], v[178:179], 0, s[20:21]
	global_load_dwordx4 v[164:167], v[2:3], off
	s_waitcnt vmcnt(7)
	ds_write_b128 v0, v[168:171] offset:24576
	v_lshl_add_u64 v[2:3], v[184:185], 0, s[20:21]
	global_load_dwordx4 v[168:171], v[2:3], off
	s_waitcnt vmcnt(7)
	ds_write_b128 v0, v[172:175] offset:57344
	v_lshl_add_u64 v[2:3], v[176:177], 0, s[20:21]
	global_load_dwordx4 v[172:175], v[2:3], off
	s_branch .Lfl_OPROJ_0_done
.Lfl_OPROJ_0_old:
	s_cmp_gt_u32 s65, 14
	s_cbranch_scc1 .LBB0_482
	s_andn2_b32 s50, 0x10000, s72
	v_add_u32_e32 v0, s50, v198
	s_waitcnt vmcnt(7)
	ds_write_b128 v0, v[144:147]
	s_waitcnt vmcnt(3)
	ds_write_b128 v0, v[152:155] offset:32768
	ds_write_b128 v0, v[148:151] offset:8192
	s_waitcnt vmcnt(2)
	ds_write_b128 v0, v[160:163] offset:40960
	ds_write_b128 v0, v[156:159] offset:16384
	s_waitcnt vmcnt(1)
	ds_write_b128 v0, v[164:167] offset:49152
	ds_write_b128 v0, v[168:171] offset:24576
	s_waitcnt vmcnt(0)
	ds_write_b128 v0, v[172:175] offset:57344

.Lfl_OPROJ_0_done:
.LBB0_484:
	s_andn2_saveexec_b64 s[48:49], s[48:49]
	s_cbranch_execz .LBB0_486
	s_and_b32 s50, s72, 0x10000
	v_add_u32_e32 v0, s50, v192
	v_or_b32_e32 v2, s50, v193
	v_add_u32_e32 v14, v0, v194
	v_add_u32_e32 v15, v0, v195
	v_add_u32_e32 v199, v0, v196
	v_add_u32_e32 v0, v0, v197
	v_add_u32_e32 v205, v2, v194
	v_add_u32_e32 v228, v2, v195
	v_add_u32_e32 v250, v2, v196
	v_add_u32_e32 v251, v2, v197
	s_setprio 1
	ds_read_b128 v[2:5], v14 offset:0
	ds_read_b128 v[6:9], v14 offset:4096
	ds_read_b128 v[10:13], v14 offset:8192
	ds_read_b128 v[214:217], v14 offset:12288
	ds_read_b128 v[246:249], v205 offset:0
	ds_read_b128 v[208:211], v205 offset:4096
	ds_read_b128 v[230:233], v15 offset:0
	ds_read_b128 v[234:237], v15 offset:4096
	ds_read_b128 v[238:241], v15 offset:8192
	ds_read_b128 v[242:245], v15 offset:12288
	s_waitcnt lgkmcnt(4)
	v_mfma_f32_32x32x16_bf16 v[128:143], v[2:5], v[246:249], v[128:143]
	v_mfma_f32_32x32x16_bf16 v[96:111], v[6:9], v[246:249], v[96:111]
	v_mfma_f32_32x32x16_bf16 v[64:79], v[10:13], v[246:249], v[64:79]
	v_mfma_f32_32x32x16_bf16 v[32:47], v[214:217], v[246:249], v[32:47]
	ds_read_b128 v[246:249], v228 offset:0
	v_mfma_f32_32x32x16_bf16 v[112:127], v[2:5], v[208:211], v[112:127]
	v_mfma_f32_32x32x16_bf16 v[80:95], v[6:9], v[208:211], v[80:95]
	v_mfma_f32_32x32x16_bf16 v[48:63], v[10:13], v[208:211], v[48:63]
	v_mfma_f32_32x32x16_bf16 v[16:31], v[214:217], v[208:211], v[16:31]
	ds_read_b128 v[208:211], v228 offset:4096
	ds_read_b128 v[2:5], v199 offset:0
	ds_read_b128 v[6:9], v199 offset:4096
	ds_read_b128 v[10:13], v199 offset:8192
	ds_read_b128 v[214:217], v199 offset:12288
	s_waitcnt lgkmcnt(5)
	v_mfma_f32_32x32x16_bf16 v[128:143], v[230:233], v[246:249], v[128:143]
	v_mfma_f32_32x32x16_bf16 v[96:111], v[234:237], v[246:249], v[96:111]
	v_mfma_f32_32x32x16_bf16 v[64:79], v[238:241], v[246:249], v[64:79]
	v_mfma_f32_32x32x16_bf16 v[32:47], v[242:245], v[246:249], v[32:47]
	ds_read_b128 v[246:249], v250 offset:0
	s_waitcnt lgkmcnt(5)
	v_mfma_f32_32x32x16_bf16 v[112:127], v[230:233], v[208:211], v[112:127]
	v_mfma_f32_32x32x16_bf16 v[80:95], v[234:237], v[208:211], v[80:95]
	v_mfma_f32_32x32x16_bf16 v[48:63], v[238:241], v[208:211], v[48:63]
	v_mfma_f32_32x32x16_bf16 v[16:31], v[242:245], v[208:211], v[16:31]
	ds_read_b128 v[208:211], v250 offset:4096
	ds_read_b128 v[230:233], v0 offset:0
	ds_read_b128 v[234:237], v0 offset:4096
	ds_read_b128 v[238:241], v0 offset:8192
	ds_read_b128 v[242:245], v0 offset:12288
	s_waitcnt lgkmcnt(5)
	v_mfma_f32_32x32x16_bf16 v[128:143], v[2:5], v[246:249], v[128:143]
	v_mfma_f32_32x32x16_bf16 v[96:111], v[6:9], v[246:249], v[96:111]
	v_mfma_f32_32x32x16_bf16 v[64:79], v[10:13], v[246:249], v[64:79]
	v_mfma_f32_32x32x16_bf16 v[32:47], v[214:217], v[246:249], v[32:47]
	ds_read_b128 v[246:249], v251 offset:0
	s_waitcnt lgkmcnt(5)
	v_mfma_f32_32x32x16_bf16 v[112:127], v[2:5], v[208:211], v[112:127]
	v_mfma_f32_32x32x16_bf16 v[80:95], v[6:9], v[208:211], v[80:95]
	v_mfma_f32_32x32x16_bf16 v[48:63], v[10:13], v[208:211], v[48:63]
	v_mfma_f32_32x32x16_bf16 v[16:31], v[214:217], v[208:211], v[16:31]
	ds_read_b128 v[208:211], v251 offset:4096
	s_waitcnt lgkmcnt(1)
	v_mfma_f32_32x32x16_bf16 v[128:143], v[230:233], v[246:249], v[128:143]
	v_mfma_f32_32x32x16_bf16 v[96:111], v[234:237], v[246:249], v[96:111]
	v_mfma_f32_32x32x16_bf16 v[64:79], v[238:241], v[246:249], v[64:79]
	v_mfma_f32_32x32x16_bf16 v[32:47], v[242:245], v[246:249], v[32:47]
	s_waitcnt lgkmcnt(0)
	v_mfma_f32_32x32x16_bf16 v[112:127], v[230:233], v[208:211], v[112:127]
	v_mfma_f32_32x32x16_bf16 v[80:95], v[234:237], v[208:211], v[80:95]
	v_mfma_f32_32x32x16_bf16 v[48:63], v[238:241], v[208:211], v[48:63]
	v_mfma_f32_32x32x16_bf16 v[16:31], v[242:245], v[208:211], v[16:31]
	s_nop 15
	s_nop 7

	s_setprio 0
.LBB0_486:
	s_or_b64 exec, exec, s[48:49]
	s_and_saveexec_b64 s[48:49], s[44:45]
	s_xor_b64 s[48:49], exec, s[48:49]
	s_cbranch_execz .LBB0_491
	s_cmp_gt_u32 s65, 13
	s_cbranch_scc1 .Lfl_OPROJ_1_old
	s_add_i32 s50, s72, 0x10000
	s_and_b32 s50, s50, 0x10000
	v_add_u32_e32 v0, s50, v198
	s_waitcnt vmcnt(7)
	ds_write_b128 v0, v[144:147]
	v_lshl_add_u64 v[2:3], v[190:191], 0, s[20:21]
	global_load_dwordx4 v[144:147], v[2:3], off
	s_waitcnt vmcnt(4)
	ds_write_b128 v0, v[152:155] offset:32768
	v_lshl_add_u64 v[2:3], v[182:183], 0, s[20:21]
	global_load_dwordx4 v[152:155], v[2:3], off
	s_waitcnt vmcnt(5)
	ds_write_b128 v0, v[148:151] offset:8192
	v_lshl_add_u64 v[2:3], v[188:189], 0, s[20:21]
	global_load_dwordx4 v[148:151], v[2:3], off
	s_waitcnt vmcnt(5)
	ds_write_b128 v0, v[160:163] offset:40960
	v_lshl_add_u64 v[2:3], v[180:181], 0, s[20:21]
	global_load_dwordx4 v[160:163], v[2:3], off
	s_waitcnt vmcnt(6)
	ds_write_b128 v0, v[156:159] offset:16384
	v_lshl_add_u64 v[2:3], v[186:187], 0, s[20:21]
	global_load_dwordx4 v[156:159], v[2:3], off
	s_waitcnt vmcnt(6)
	ds_write_b128 v0, v[164:167] offset:49152
	v_lshl_add_u64 v[2:3], v[178:179], 0, s[20:21]
	global_load_dwordx4 v[164:167], v[2:3], off
	s_waitcnt vmcnt(7)
	ds_write_b128 v0, v[168:171] offset:24576
	v_lshl_add_u64 v[2:3], v[184:185], 0, s[20:21]
	global_load_dwordx4 v[168:171], v[2:3], off
	s_waitcnt vmcnt(7)
	ds_write_b128 v0, v[172:175] offset:57344
	v_lshl_add_u64 v[2:3], v[176:177], 0, s[20:21]
	global_load_dwordx4 v[172:175], v[2:3], off
	s_branch .Lfl_OPROJ_1_done
.Lfl_OPROJ_1_old:
	s_cmp_gt_u32 s65, 14
	s_cbranch_scc1 .LBB0_489
	s_add_i32 s50, s72, 0x10000
	s_and_b32 s50, s50, 0x10000
	v_add_u32_e32 v0, s50, v198
	s_waitcnt vmcnt(7)
	ds_write_b128 v0, v[144:147]
	s_waitcnt vmcnt(3)
	ds_write_b128 v0, v[152:155] offset:32768
	ds_write_b128 v0, v[148:151] offset:8192
	s_waitcnt vmcnt(2)
	ds_write_b128 v0, v[160:163] offset:40960
	ds_write_b128 v0, v[156:159] offset:16384
	s_waitcnt vmcnt(1)
	ds_write_b128 v0, v[164:167] offset:49152
	ds_write_b128 v0, v[168:171] offset:24576
	s_waitcnt vmcnt(0)
	ds_write_b128 v0, v[172:175] offset:57344

.Lfl_OPROJ_1_done:
.LBB0_491:
	s_andn2_saveexec_b64 s[48:49], s[48:49]
	s_cbranch_execz .LBB0_478
	s_and_b32 s50, s72, 0x10000
	v_add_u32_e32 v0, s50, v192
	v_or_b32_e32 v2, s50, v193
	v_add_u32_e32 v14, v0, v194
	v_add_u32_e32 v15, v0, v195
	v_add_u32_e32 v199, v0, v196
	v_add_u32_e32 v0, v0, v197
	v_add_u32_e32 v205, v2, v194
	v_add_u32_e32 v228, v2, v195
	v_add_u32_e32 v250, v2, v196
	v_add_u32_e32 v251, v2, v197
	s_setprio 1
	ds_read_b128 v[2:5], v14 offset:0
	ds_read_b128 v[6:9], v14 offset:4096
	ds_read_b128 v[10:13], v14 offset:8192
	ds_read_b128 v[208:211], v14 offset:12288
	ds_read_b128 v[242:245], v205 offset:0
	ds_read_b128 v[246:249], v205 offset:4096
	ds_read_b128 v[214:217], v15 offset:0
	ds_read_b128 v[230:233], v15 offset:4096
	ds_read_b128 v[234:237], v15 offset:8192
	ds_read_b128 v[238:241], v15 offset:12288
	s_waitcnt lgkmcnt(4)
	v_mfma_f32_32x32x16_bf16 v[128:143], v[2:5], v[242:245], v[128:143]
	v_mfma_f32_32x32x16_bf16 v[96:111], v[6:9], v[242:245], v[96:111]
	v_mfma_f32_32x32x16_bf16 v[64:79], v[10:13], v[242:245], v[64:79]
	v_mfma_f32_32x32x16_bf16 v[32:47], v[208:211], v[242:245], v[32:47]
	ds_read_b128 v[242:245], v228 offset:0
	v_mfma_f32_32x32x16_bf16 v[112:127], v[2:5], v[246:249], v[112:127]
	v_mfma_f32_32x32x16_bf16 v[80:95], v[6:9], v[246:249], v[80:95]
	v_mfma_f32_32x32x16_bf16 v[48:63], v[10:13], v[246:249], v[48:63]
	v_mfma_f32_32x32x16_bf16 v[16:31], v[208:211], v[246:249], v[16:31]
	ds_read_b128 v[246:249], v228 offset:4096
	ds_read_b128 v[2:5], v199 offset:0
	ds_read_b128 v[6:9], v199 offset:4096
	ds_read_b128 v[10:13], v199 offset:8192
	ds_read_b128 v[208:211], v199 offset:12288
	s_waitcnt lgkmcnt(5)
	v_mfma_f32_32x32x16_bf16 v[128:143], v[214:217], v[242:245], v[128:143]
	v_mfma_f32_32x32x16_bf16 v[96:111], v[230:233], v[242:245], v[96:111]
	v_mfma_f32_32x32x16_bf16 v[64:79], v[234:237], v[242:245], v[64:79]
	v_mfma_f32_32x32x16_bf16 v[32:47], v[238:241], v[242:245], v[32:47]
	ds_read_b128 v[242:245], v250 offset:0
	s_waitcnt lgkmcnt(5)
	v_mfma_f32_32x32x16_bf16 v[112:127], v[214:217], v[246:249], v[112:127]
	v_mfma_f32_32x32x16_bf16 v[80:95], v[230:233], v[246:249], v[80:95]
	v_mfma_f32_32x32x16_bf16 v[48:63], v[234:237], v[246:249], v[48:63]
	v_mfma_f32_32x32x16_bf16 v[16:31], v[238:241], v[246:249], v[16:31]
	ds_read_b128 v[246:249], v250 offset:4096
	ds_read_b128 v[214:217], v0 offset:0
	ds_read_b128 v[230:233], v0 offset:4096
	ds_read_b128 v[234:237], v0 offset:8192
	ds_read_b128 v[238:241], v0 offset:12288
	s_waitcnt lgkmcnt(5)
	v_mfma_f32_32x32x16_bf16 v[128:143], v[2:5], v[242:245], v[128:143]
	v_mfma_f32_32x32x16_bf16 v[96:111], v[6:9], v[242:245], v[96:111]
	v_mfma_f32_32x32x16_bf16 v[64:79], v[10:13], v[242:245], v[64:79]
	v_mfma_f32_32x32x16_bf16 v[32:47], v[208:211], v[242:245], v[32:47]
	ds_read_b128 v[242:245], v251 offset:0
	s_waitcnt lgkmcnt(5)
	v_mfma_f32_32x32x16_bf16 v[112:127], v[2:5], v[246:249], v[112:127]
	v_mfma_f32_32x32x16_bf16 v[80:95], v[6:9], v[246:249], v[80:95]
	v_mfma_f32_32x32x16_bf16 v[48:63], v[10:13], v[246:249], v[48:63]
	v_mfma_f32_32x32x16_bf16 v[16:31], v[208:211], v[246:249], v[16:31]
	ds_read_b128 v[246:249], v251 offset:4096
	s_waitcnt lgkmcnt(1)
	v_mfma_f32_32x32x16_bf16 v[128:143], v[214:217], v[242:245], v[128:143]
	v_mfma_f32_32x32x16_bf16 v[96:111], v[230:233], v[242:245], v[96:111]
	v_mfma_f32_32x32x16_bf16 v[64:79], v[234:237], v[242:245], v[64:79]
	v_mfma_f32_32x32x16_bf16 v[32:47], v[238:241], v[242:245], v[32:47]
	s_waitcnt lgkmcnt(0)
	v_mfma_f32_32x32x16_bf16 v[112:127], v[214:217], v[246:249], v[112:127]
	v_mfma_f32_32x32x16_bf16 v[80:95], v[230:233], v[246:249], v[80:95]
	v_mfma_f32_32x32x16_bf16 v[48:63], v[234:237], v[246:249], v[48:63]
	v_mfma_f32_32x32x16_bf16 v[16:31], v[238:241], v[246:249], v[16:31]
	s_nop 15
	s_nop 7

	s_setprio 0
	s_branch .LBB0_478

.LBB0_576:
	s_and_saveexec_b64 s[30:31], s[42:43]
	s_xor_b64 s[30:31], exec, s[30:31]
	s_cbranch_execz .LBB0_581
	s_cmp_gt_u32 s29, 13
	s_cbranch_scc1 .Lfl_QKV_0_old
	s_andn2_b32 s46, 0x10000, s27
	v_add_u32_e32 v0, s46, v201
	s_waitcnt vmcnt(7)
	ds_write_b128 v0, v[144:147]
	v_lshl_add_u64 v[2:3], v[190:191], 0, s[20:21]
	global_load_dwordx4 v[144:147], v[2:3], off
	s_waitcnt vmcnt(4)
	ds_write_b128 v0, v[152:155] offset:32768
	v_lshl_add_u64 v[2:3], v[182:183], 0, s[20:21]
	global_load_dwordx4 v[152:155], v[2:3], off
	s_waitcnt vmcnt(5)
	ds_write_b128 v0, v[148:151] offset:8192
	v_lshl_add_u64 v[2:3], v[188:189], 0, s[20:21]
	global_load_dwordx4 v[148:151], v[2:3], off
	s_waitcnt vmcnt(5)
	ds_write_b128 v0, v[160:163] offset:40960
	v_lshl_add_u64 v[2:3], v[180:181], 0, s[20:21]
	global_load_dwordx4 v[160:163], v[2:3], off
	s_waitcnt vmcnt(6)
	ds_write_b128 v0, v[156:159] offset:16384
	v_lshl_add_u64 v[2:3], v[186:187], 0, s[20:21]
	global_load_dwordx4 v[156:159], v[2:3], off
	s_waitcnt vmcnt(6)
	ds_write_b128 v0, v[164:167] offset:49152
	v_lshl_add_u64 v[2:3], v[178:179], 0, s[20:21]
	global_load_dwordx4 v[164:167], v[2:3], off
	s_waitcnt vmcnt(7)
	ds_write_b128 v0, v[168:171] offset:24576
	v_lshl_add_u64 v[2:3], v[184:185], 0, s[20:21]
	global_load_dwordx4 v[168:171], v[2:3], off
	s_waitcnt vmcnt(7)
	ds_write_b128 v0, v[172:175] offset:57344
	v_lshl_add_u64 v[2:3], v[176:177], 0, s[20:21]
	global_load_dwordx4 v[172:175], v[2:3], off
	s_branch .Lfl_QKV_0_done
.Lfl_QKV_0_old:
	s_cmpk_eq_i32 s20, 0x780
	s_cbranch_scc1 .LBB0_579
	s_andn2_b32 s46, 0x10000, s27
	v_add_u32_e32 v0, s46, v201
	s_waitcnt vmcnt(7)
	ds_write_b128 v0, v[144:147]
	s_waitcnt vmcnt(3)
	ds_write_b128 v0, v[152:155] offset:32768
	ds_write_b128 v0, v[148:151] offset:8192
	s_waitcnt vmcnt(2)
	ds_write_b128 v0, v[160:163] offset:40960
	ds_write_b128 v0, v[156:159] offset:16384
	s_waitcnt vmcnt(1)
	ds_write_b128 v0, v[164:167] offset:49152
	ds_write_b128 v0, v[168:171] offset:24576
	s_waitcnt vmcnt(0)
	ds_write_b128 v0, v[172:175] offset:57344

.Lfl_QKV_0_done:
.LBB0_581:
	s_andn2_saveexec_b64 s[30:31], s[30:31]
	s_cbranch_execz .LBB0_583
	s_and_b32 s46, s27, 0x10000
	v_add_u32_e32 v0, s46, v195
	v_or_b32_e32 v2, s46, v196
	v_add_u32_e32 v14, v0, v197
	v_add_u32_e32 v15, v0, v198
	v_add_u32_e32 v208, v0, v199
	v_add_u32_e32 v0, v0, v200
	v_add_u32_e32 v209, v2, v197
	v_add_u32_e32 v210, v2, v198
	v_add_u32_e32 v211, v2, v199
	v_add_u32_e32 v214, v2, v200
	s_setprio 1
	ds_read_b128 v[2:5], v14 offset:0
	ds_read_b128 v[6:9], v14 offset:4096
	ds_read_b128 v[10:13], v14 offset:8192
	ds_read_b128 v[202:205], v14 offset:12288
	ds_read_b128 v[244:247], v209 offset:0
	ds_read_b128 v[248:251], v209 offset:4096
	ds_read_b128 v[228:231], v15 offset:0
	ds_read_b128 v[232:235], v15 offset:4096
	ds_read_b128 v[236:239], v15 offset:8192
	ds_read_b128 v[240:243], v15 offset:12288
	s_waitcnt lgkmcnt(4)
	v_mfma_f32_32x32x16_bf16 v[128:143], v[2:5], v[244:247], v[128:143]
	v_mfma_f32_32x32x16_bf16 v[96:111], v[6:9], v[244:247], v[96:111]
	v_mfma_f32_32x32x16_bf16 v[64:79], v[10:13], v[244:247], v[64:79]
	v_mfma_f32_32x32x16_bf16 v[32:47], v[202:205], v[244:247], v[32:47]
	ds_read_b128 v[244:247], v210 offset:0
	v_mfma_f32_32x32x16_bf16 v[112:127], v[2:5], v[248:251], v[112:127]
	v_mfma_f32_32x32x16_bf16 v[80:95], v[6:9], v[248:251], v[80:95]
	v_mfma_f32_32x32x16_bf16 v[48:63], v[10:13], v[248:251], v[48:63]
	v_mfma_f32_32x32x16_bf16 v[16:31], v[202:205], v[248:251], v[16:31]
	ds_read_b128 v[248:251], v210 offset:4096
	ds_read_b128 v[2:5], v208 offset:0
	ds_read_b128 v[6:9], v208 offset:4096
	ds_read_b128 v[10:13], v208 offset:8192
	ds_read_b128 v[202:205], v208 offset:12288
	s_waitcnt lgkmcnt(5)
	v_mfma_f32_32x32x16_bf16 v[128:143], v[228:231], v[244:247], v[128:143]
	v_mfma_f32_32x32x16_bf16 v[96:111], v[232:235], v[244:247], v[96:111]
	v_mfma_f32_32x32x16_bf16 v[64:79], v[236:239], v[244:247], v[64:79]
	v_mfma_f32_32x32x16_bf16 v[32:47], v[240:243], v[244:247], v[32:47]
	ds_read_b128 v[244:247], v211 offset:0
	s_waitcnt lgkmcnt(5)
	v_mfma_f32_32x32x16_bf16 v[112:127], v[228:231], v[248:251], v[112:127]
	v_mfma_f32_32x32x16_bf16 v[80:95], v[232:235], v[248:251], v[80:95]
	v_mfma_f32_32x32x16_bf16 v[48:63], v[236:239], v[248:251], v[48:63]
	v_mfma_f32_32x32x16_bf16 v[16:31], v[240:243], v[248:251], v[16:31]
	ds_read_b128 v[248:251], v211 offset:4096
	ds_read_b128 v[228:231], v0 offset:0
	ds_read_b128 v[232:235], v0 offset:4096
	ds_read_b128 v[236:239], v0 offset:8192
	ds_read_b128 v[240:243], v0 offset:12288
	s_waitcnt lgkmcnt(5)
	v_mfma_f32_32x32x16_bf16 v[128:143], v[2:5], v[244:247], v[128:143]
	v_mfma_f32_32x32x16_bf16 v[96:111], v[6:9], v[244:247], v[96:111]
	v_mfma_f32_32x32x16_bf16 v[64:79], v[10:13], v[244:247], v[64:79]
	v_mfma_f32_32x32x16_bf16 v[32:47], v[202:205], v[244:247], v[32:47]
	ds_read_b128 v[244:247], v214 offset:0
	s_waitcnt lgkmcnt(5)
	v_mfma_f32_32x32x16_bf16 v[112:127], v[2:5], v[248:251], v[112:127]
	v_mfma_f32_32x32x16_bf16 v[80:95], v[6:9], v[248:251], v[80:95]
	v_mfma_f32_32x32x16_bf16 v[48:63], v[10:13], v[248:251], v[48:63]
	v_mfma_f32_32x32x16_bf16 v[16:31], v[202:205], v[248:251], v[16:31]
	ds_read_b128 v[248:251], v214 offset:4096
	s_waitcnt lgkmcnt(1)
	v_mfma_f32_32x32x16_bf16 v[128:143], v[228:231], v[244:247], v[128:143]
	v_mfma_f32_32x32x16_bf16 v[96:111], v[232:235], v[244:247], v[96:111]
	v_mfma_f32_32x32x16_bf16 v[64:79], v[236:239], v[244:247], v[64:79]
	v_mfma_f32_32x32x16_bf16 v[32:47], v[240:243], v[244:247], v[32:47]
	s_waitcnt lgkmcnt(0)
	v_mfma_f32_32x32x16_bf16 v[112:127], v[228:231], v[248:251], v[112:127]
	v_mfma_f32_32x32x16_bf16 v[80:95], v[232:235], v[248:251], v[80:95]
	v_mfma_f32_32x32x16_bf16 v[48:63], v[236:239], v[248:251], v[48:63]
	v_mfma_f32_32x32x16_bf16 v[16:31], v[240:243], v[248:251], v[16:31]
	s_nop 15
	s_nop 7

	s_setprio 0
.LBB0_583:
	s_or_b64 exec, exec, s[30:31]
	s_and_saveexec_b64 s[30:31], s[44:45]
	s_xor_b64 s[30:31], exec, s[30:31]
	s_cbranch_execz .LBB0_588
	s_cmp_gt_u32 s29, 13
	s_cbranch_scc1 .Lfl_QKV_1_old
	s_andn2_b32 s46, 0x10000, s27
	v_add_u32_e32 v0, s46, v201
	s_waitcnt vmcnt(7)
	ds_write_b128 v0, v[144:147]
	v_lshl_add_u64 v[2:3], v[190:191], 0, s[20:21]
	global_load_dwordx4 v[144:147], v[2:3], off
	s_waitcnt vmcnt(4)
	ds_write_b128 v0, v[152:155] offset:32768
	v_lshl_add_u64 v[2:3], v[182:183], 0, s[20:21]
	global_load_dwordx4 v[152:155], v[2:3], off
	s_waitcnt vmcnt(5)
	ds_write_b128 v0, v[148:151] offset:8192
	v_lshl_add_u64 v[2:3], v[188:189], 0, s[20:21]
	global_load_dwordx4 v[148:151], v[2:3], off
	s_waitcnt vmcnt(5)
	ds_write_b128 v0, v[160:163] offset:40960
	v_lshl_add_u64 v[2:3], v[180:181], 0, s[20:21]
	global_load_dwordx4 v[160:163], v[2:3], off
	s_waitcnt vmcnt(6)
	ds_write_b128 v0, v[156:159] offset:16384
	v_lshl_add_u64 v[2:3], v[186:187], 0, s[20:21]
	global_load_dwordx4 v[156:159], v[2:3], off
	s_waitcnt vmcnt(6)
	ds_write_b128 v0, v[164:167] offset:49152
	v_lshl_add_u64 v[2:3], v[178:179], 0, s[20:21]
	global_load_dwordx4 v[164:167], v[2:3], off
	s_waitcnt vmcnt(7)
	ds_write_b128 v0, v[168:171] offset:24576
	v_lshl_add_u64 v[2:3], v[184:185], 0, s[20:21]
	global_load_dwordx4 v[168:171], v[2:3], off
	s_waitcnt vmcnt(7)
	ds_write_b128 v0, v[172:175] offset:57344
	v_lshl_add_u64 v[2:3], v[176:177], 0, s[20:21]
	global_load_dwordx4 v[172:175], v[2:3], off
	s_branch .Lfl_QKV_1_done

.Lfl_QKV_1_done:
.LBB0_588:
	s_andn2_saveexec_b64 s[30:31], s[30:31]
	s_cbranch_execz .LBB0_575
	s_and_b32 s46, s27, 0x10000
	v_add_u32_e32 v0, s46, v195
	v_or_b32_e32 v2, s46, v196
	v_add_u32_e32 v14, v0, v197
	v_add_u32_e32 v15, v0, v198
	v_add_u32_e32 v208, v0, v199
	v_add_u32_e32 v0, v0, v200
	v_add_u32_e32 v209, v2, v197
	v_add_u32_e32 v210, v2, v198
	v_add_u32_e32 v211, v2, v199
	v_add_u32_e32 v214, v2, v200
	s_setprio 1
	ds_read_b128 v[2:5], v14 offset:0
	ds_read_b128 v[6:9], v14 offset:4096
	ds_read_b128 v[10:13], v14 offset:8192
	ds_read_b128 v[202:205], v14 offset:12288
	ds_read_b128 v[244:247], v209 offset:0
	ds_read_b128 v[248:251], v209 offset:4096
	ds_read_b128 v[228:231], v15 offset:0
	ds_read_b128 v[232:235], v15 offset:4096
	ds_read_b128 v[236:239], v15 offset:8192
	ds_read_b128 v[240:243], v15 offset:12288
	s_waitcnt lgkmcnt(4)
	v_mfma_f32_32x32x16_bf16 v[128:143], v[2:5], v[244:247], v[128:143]
	v_mfma_f32_32x32x16_bf16 v[96:111], v[6:9], v[244:247], v[96:111]
	v_mfma_f32_32x32x16_bf16 v[64:79], v[10:13], v[244:247], v[64:79]
	v_mfma_f32_32x32x16_bf16 v[32:47], v[202:205], v[244:247], v[32:47]
	ds_read_b128 v[244:247], v210 offset:0
	v_mfma_f32_32x32x16_bf16 v[112:127], v[2:5], v[248:251], v[112:127]
	v_mfma_f32_32x32x16_bf16 v[80:95], v[6:9], v[248:251], v[80:95]
	v_mfma_f32_32x32x16_bf16 v[48:63], v[10:13], v[248:251], v[48:63]
	v_mfma_f32_32x32x16_bf16 v[16:31], v[202:205], v[248:251], v[16:31]
	ds_read_b128 v[248:251], v210 offset:4096
	ds_read_b128 v[2:5], v208 offset:0
	ds_read_b128 v[6:9], v208 offset:4096
	ds_read_b128 v[10:13], v208 offset:8192
	ds_read_b128 v[202:205], v208 offset:12288
	s_waitcnt lgkmcnt(5)
	v_mfma_f32_32x32x16_bf16 v[128:143], v[228:231], v[244:247], v[128:143]
	v_mfma_f32_32x32x16_bf16 v[96:111], v[232:235], v[244:247], v[96:111]
	v_mfma_f32_32x32x16_bf16 v[64:79], v[236:239], v[244:247], v[64:79]
	v_mfma_f32_32x32x16_bf16 v[32:47], v[240:243], v[244:247], v[32:47]
	ds_read_b128 v[244:247], v211 offset:0
	s_waitcnt lgkmcnt(5)
	v_mfma_f32_32x32x16_bf16 v[112:127], v[228:231], v[248:251], v[112:127]
	v_mfma_f32_32x32x16_bf16 v[80:95], v[232:235], v[248:251], v[80:95]
	v_mfma_f32_32x32x16_bf16 v[48:63], v[236:239], v[248:251], v[48:63]
	v_mfma_f32_32x32x16_bf16 v[16:31], v[240:243], v[248:251], v[16:31]
	ds_read_b128 v[248:251], v211 offset:4096
	ds_read_b128 v[228:231], v0 offset:0
	ds_read_b128 v[232:235], v0 offset:4096
	ds_read_b128 v[236:239], v0 offset:8192
	ds_read_b128 v[240:243], v0 offset:12288
	s_waitcnt lgkmcnt(5)
	v_mfma_f32_32x32x16_bf16 v[128:143], v[2:5], v[244:247], v[128:143]
	v_mfma_f32_32x32x16_bf16 v[96:111], v[6:9], v[244:247], v[96:111]
	v_mfma_f32_32x32x16_bf16 v[64:79], v[10:13], v[244:247], v[64:79]
	v_mfma_f32_32x32x16_bf16 v[32:47], v[202:205], v[244:247], v[32:47]
	ds_read_b128 v[244:247], v214 offset:0
	s_waitcnt lgkmcnt(5)
	v_mfma_f32_32x32x16_bf16 v[112:127], v[2:5], v[248:251], v[112:127]
	v_mfma_f32_32x32x16_bf16 v[80:95], v[6:9], v[248:251], v[80:95]
	v_mfma_f32_32x32x16_bf16 v[48:63], v[10:13], v[248:251], v[48:63]
	v_mfma_f32_32x32x16_bf16 v[16:31], v[202:205], v[248:251], v[16:31]
	ds_read_b128 v[248:251], v214 offset:4096
	s_waitcnt lgkmcnt(1)
	v_mfma_f32_32x32x16_bf16 v[128:143], v[228:231], v[244:247], v[128:143]
	v_mfma_f32_32x32x16_bf16 v[96:111], v[232:235], v[244:247], v[96:111]
	v_mfma_f32_32x32x16_bf16 v[64:79], v[236:239], v[244:247], v[64:79]
	v_mfma_f32_32x32x16_bf16 v[32:47], v[240:243], v[244:247], v[32:47]
	s_waitcnt lgkmcnt(0)
	v_mfma_f32_32x32x16_bf16 v[112:127], v[228:231], v[248:251], v[112:127]
	v_mfma_f32_32x32x16_bf16 v[80:95], v[232:235], v[248:251], v[80:95]
	v_mfma_f32_32x32x16_bf16 v[48:63], v[236:239], v[248:251], v[48:63]
	v_mfma_f32_32x32x16_bf16 v[16:31], v[240:243], v[248:251], v[16:31]
	s_nop 15
	s_nop 7

	s_setprio 0
	s_branch .LBB0_575

.LBB0_598:
	s_and_saveexec_b64 s[22:23], s[42:43]
	s_xor_b64 s[22:23], exec, s[22:23]
	s_cbranch_execz .LBB0_603
	s_cmp_ge_u32 s49, s54
	s_cbranch_scc1 .Lfl_MLA_DOWN_0_old
	s_add_i32 s56, s53, 0x10000
	s_and_b32 s56, s56, 0x10000
	v_add_u32_e32 v0, s56, v201
	s_waitcnt vmcnt(7)
	ds_write_b128 v0, v[144:147]
	v_lshl_add_u64 v[2:3], v[176:177], 0, s[20:21]
	global_load_dwordx4 v[144:147], v[2:3], off
	s_waitcnt vmcnt(7)
	ds_write_b128 v0, v[148:151] offset:32768
	v_lshl_add_u64 v[2:3], v[184:185], 0, s[20:21]
	global_load_dwordx4 v[148:151], v[2:3], off
	s_waitcnt vmcnt(7)
	ds_write_b128 v0, v[152:155] offset:8192
	v_lshl_add_u64 v[2:3], v[178:179], 0, s[20:21]
	global_load_dwordx4 v[152:155], v[2:3], off
	s_waitcnt vmcnt(7)
	ds_write_b128 v0, v[156:159] offset:40960
	v_lshl_add_u64 v[2:3], v[186:187], 0, s[20:21]
	global_load_dwordx4 v[156:159], v[2:3], off
	s_waitcnt vmcnt(7)
	ds_write_b128 v0, v[160:163] offset:16384
	v_lshl_add_u64 v[2:3], v[180:181], 0, s[20:21]
	global_load_dwordx4 v[160:163], v[2:3], off
	s_waitcnt vmcnt(7)
	ds_write_b128 v0, v[164:167] offset:49152
	v_lshl_add_u64 v[2:3], v[188:189], 0, s[20:21]
	global_load_dwordx4 v[164:167], v[2:3], off
	s_waitcnt vmcnt(7)
	ds_write_b128 v0, v[168:171] offset:24576
	v_lshl_add_u64 v[2:3], v[182:183], 0, s[20:21]
	global_load_dwordx4 v[168:171], v[2:3], off
	s_waitcnt vmcnt(7)
	ds_write_b128 v0, v[172:175] offset:57344
	v_lshl_add_u64 v[2:3], v[190:191], 0, s[20:21]
	global_load_dwordx4 v[172:175], v[2:3], off
	s_branch .Lfl_MLA_DOWN_0_done
.Lfl_MLA_DOWN_0_old:
	s_add_i32 s56, s49, -1
	s_cmp_ge_u32 s56, s54
	s_cbranch_scc1 .LBB0_601
	s_add_i32 s56, s53, 0x10000
	s_and_b32 s56, s56, 0x10000
	v_add_u32_e32 v0, s56, v201
	s_waitcnt vmcnt(7)
	ds_write_b128 v0, v[144:147]
	s_waitcnt vmcnt(6)
	ds_write_b128 v0, v[148:151] offset:32768
	s_waitcnt vmcnt(5)
	ds_write_b128 v0, v[152:155] offset:8192
	s_waitcnt vmcnt(4)
	ds_write_b128 v0, v[156:159] offset:40960
	s_waitcnt vmcnt(3)
	ds_write_b128 v0, v[160:163] offset:16384
	s_waitcnt vmcnt(2)
	ds_write_b128 v0, v[164:167] offset:49152
	s_waitcnt vmcnt(1)
	ds_write_b128 v0, v[168:171] offset:24576
	s_waitcnt vmcnt(0)
	ds_write_b128 v0, v[172:175] offset:57344

.Lfl_MLA_DOWN_0_done:
.LBB0_603:
	s_andn2_saveexec_b64 s[22:23], s[22:23]
	s_cbranch_execz .LBB0_605
	s_and_b32 s56, s53, 0x10000
	v_add_u32_e32 v0, s56, v195
	v_or_b32_e32 v2, s56, v196
	v_add_u32_e32 v14, v0, v197
	v_add_u32_e32 v15, v0, v198
	v_add_u32_e32 v203, v0, v199
	v_add_u32_e32 v0, v0, v200
	v_add_u32_e32 v204, v2, v197
	v_add_u32_e32 v205, v2, v198
	v_add_u32_e32 v208, v2, v199
	v_add_u32_e32 v209, v2, v200
	s_setprio 1
	ds_read_b128 v[2:5], v14 offset:0
	ds_read_b128 v[6:9], v14 offset:4096
	ds_read_b128 v[10:13], v14 offset:8192
	ds_read_b128 v[228:231], v14 offset:12288
	ds_read_b128 v[248:251], v204 offset:0
	ds_read_b128 v[214:217], v204 offset:4096
	ds_read_b128 v[232:235], v15 offset:0
	ds_read_b128 v[236:239], v15 offset:4096
	ds_read_b128 v[240:243], v15 offset:8192
	ds_read_b128 v[244:247], v15 offset:12288
	s_waitcnt lgkmcnt(4)
	v_mfma_f32_32x32x16_bf16 v[128:143], v[2:5], v[248:251], v[128:143]
	v_mfma_f32_32x32x16_bf16 v[96:111], v[6:9], v[248:251], v[96:111]
	v_mfma_f32_32x32x16_bf16 v[64:79], v[10:13], v[248:251], v[64:79]
	v_mfma_f32_32x32x16_bf16 v[32:47], v[228:231], v[248:251], v[32:47]
	ds_read_b128 v[248:251], v205 offset:0
	v_mfma_f32_32x32x16_bf16 v[112:127], v[2:5], v[214:217], v[112:127]
	v_mfma_f32_32x32x16_bf16 v[80:95], v[6:9], v[214:217], v[80:95]
	v_mfma_f32_32x32x16_bf16 v[48:63], v[10:13], v[214:217], v[48:63]
	v_mfma_f32_32x32x16_bf16 v[16:31], v[228:231], v[214:217], v[16:31]
	ds_read_b128 v[214:217], v205 offset:4096
	ds_read_b128 v[2:5], v203 offset:0
	ds_read_b128 v[6:9], v203 offset:4096
	ds_read_b128 v[10:13], v203 offset:8192
	ds_read_b128 v[228:231], v203 offset:12288
	s_waitcnt lgkmcnt(5)
	v_mfma_f32_32x32x16_bf16 v[128:143], v[232:235], v[248:251], v[128:143]
	v_mfma_f32_32x32x16_bf16 v[96:111], v[236:239], v[248:251], v[96:111]
	v_mfma_f32_32x32x16_bf16 v[64:79], v[240:243], v[248:251], v[64:79]
	v_mfma_f32_32x32x16_bf16 v[32:47], v[244:247], v[248:251], v[32:47]
	ds_read_b128 v[248:251], v208 offset:0
	s_waitcnt lgkmcnt(5)
	v_mfma_f32_32x32x16_bf16 v[112:127], v[232:235], v[214:217], v[112:127]
	v_mfma_f32_32x32x16_bf16 v[80:95], v[236:239], v[214:217], v[80:95]
	v_mfma_f32_32x32x16_bf16 v[48:63], v[240:243], v[214:217], v[48:63]
	v_mfma_f32_32x32x16_bf16 v[16:31], v[244:247], v[214:217], v[16:31]
	ds_read_b128 v[214:217], v208 offset:4096
	ds_read_b128 v[232:235], v0 offset:0
	ds_read_b128 v[236:239], v0 offset:4096
	ds_read_b128 v[240:243], v0 offset:8192
	ds_read_b128 v[244:247], v0 offset:12288
	s_waitcnt lgkmcnt(5)
	v_mfma_f32_32x32x16_bf16 v[128:143], v[2:5], v[248:251], v[128:143]
	v_mfma_f32_32x32x16_bf16 v[96:111], v[6:9], v[248:251], v[96:111]
	v_mfma_f32_32x32x16_bf16 v[64:79], v[10:13], v[248:251], v[64:79]
	v_mfma_f32_32x32x16_bf16 v[32:47], v[228:231], v[248:251], v[32:47]
	ds_read_b128 v[248:251], v209 offset:0
	s_waitcnt lgkmcnt(5)
	v_mfma_f32_32x32x16_bf16 v[112:127], v[2:5], v[214:217], v[112:127]
	v_mfma_f32_32x32x16_bf16 v[80:95], v[6:9], v[214:217], v[80:95]
	v_mfma_f32_32x32x16_bf16 v[48:63], v[10:13], v[214:217], v[48:63]
	v_mfma_f32_32x32x16_bf16 v[16:31], v[228:231], v[214:217], v[16:31]
	ds_read_b128 v[214:217], v209 offset:4096
	s_waitcnt lgkmcnt(1)
	v_mfma_f32_32x32x16_bf16 v[128:143], v[232:235], v[248:251], v[128:143]
	v_mfma_f32_32x32x16_bf16 v[96:111], v[236:239], v[248:251], v[96:111]
	v_mfma_f32_32x32x16_bf16 v[64:79], v[240:243], v[248:251], v[64:79]
	v_mfma_f32_32x32x16_bf16 v[32:47], v[244:247], v[248:251], v[32:47]
	s_waitcnt lgkmcnt(0)
	v_mfma_f32_32x32x16_bf16 v[112:127], v[232:235], v[214:217], v[112:127]
	v_mfma_f32_32x32x16_bf16 v[80:95], v[236:239], v[214:217], v[80:95]
	v_mfma_f32_32x32x16_bf16 v[48:63], v[240:243], v[214:217], v[48:63]
	v_mfma_f32_32x32x16_bf16 v[16:31], v[244:247], v[214:217], v[16:31]
	s_nop 15
	s_nop 7

	s_setprio 0
.LBB0_605:
	s_or_b64 exec, exec, s[22:23]
	s_and_saveexec_b64 s[22:23], s[44:45]
	s_xor_b64 s[22:23], exec, s[22:23]
	s_cbranch_execz .LBB0_611
	s_cmp_ge_u32 s49, s54
	s_cbranch_scc1 .Lfl_MLA_DOWN_1_old
	s_add_i32 s56, s53, 0x10000
	s_and_b32 s56, s56, 0x10000
	v_add_u32_e32 v0, s56, v201
	s_waitcnt vmcnt(7)
	ds_write_b128 v0, v[144:147]
	v_lshl_add_u64 v[2:3], v[176:177], 0, s[20:21]
	global_load_dwordx4 v[144:147], v[2:3], off
	s_waitcnt vmcnt(7)
	ds_write_b128 v0, v[148:151] offset:32768
	v_lshl_add_u64 v[2:3], v[184:185], 0, s[20:21]
	global_load_dwordx4 v[148:151], v[2:3], off
	s_waitcnt vmcnt(7)
	ds_write_b128 v0, v[152:155] offset:8192
	v_lshl_add_u64 v[2:3], v[178:179], 0, s[20:21]
	global_load_dwordx4 v[152:155], v[2:3], off
	s_waitcnt vmcnt(7)
	ds_write_b128 v0, v[156:159] offset:40960
	v_lshl_add_u64 v[2:3], v[186:187], 0, s[20:21]
	global_load_dwordx4 v[156:159], v[2:3], off
	s_waitcnt vmcnt(7)
	ds_write_b128 v0, v[160:163] offset:16384
	v_lshl_add_u64 v[2:3], v[180:181], 0, s[20:21]
	global_load_dwordx4 v[160:163], v[2:3], off
	s_waitcnt vmcnt(7)
	ds_write_b128 v0, v[164:167] offset:49152
	v_lshl_add_u64 v[2:3], v[188:189], 0, s[20:21]
	global_load_dwordx4 v[164:167], v[2:3], off
	s_waitcnt vmcnt(7)
	ds_write_b128 v0, v[168:171] offset:24576
	v_lshl_add_u64 v[2:3], v[182:183], 0, s[20:21]
	global_load_dwordx4 v[168:171], v[2:3], off
	s_waitcnt vmcnt(7)
	ds_write_b128 v0, v[172:175] offset:57344
	v_lshl_add_u64 v[2:3], v[190:191], 0, s[20:21]
	global_load_dwordx4 v[172:175], v[2:3], off
	s_branch .Lfl_MLA_DOWN_1_done

.Lfl_MLA_DOWN_1_done:
.LBB0_610:
	v_add_u32_e32 v202, 1, v202

.LBB0_714:
	s_and_saveexec_b64 s[20:21], s[42:43]
	s_xor_b64 s[20:21], exec, s[20:21]
	s_cbranch_execz .LBB0_719
	s_cmp_gt_u32 s27, 13
	s_cbranch_scc1 .Lfl_MLA_UP_0_old
	s_andn2_b32 s48, 0x10000, s26
	v_add_u32_e32 v0, s48, v201
	s_waitcnt vmcnt(7)
	ds_write_b128 v0, v[144:147]
	v_lshl_add_u64 v[2:3], v[190:191], 0, s[22:23]
	global_load_dwordx4 v[144:147], v[2:3], off
	s_waitcnt vmcnt(7)
	ds_write_b128 v0, v[148:151] offset:32768
	v_lshl_add_u64 v[2:3], v[182:183], 0, s[22:23]
	global_load_dwordx4 v[148:151], v[2:3], off
	s_waitcnt vmcnt(7)
	ds_write_b128 v0, v[152:155] offset:8192
	v_lshl_add_u64 v[2:3], v[188:189], 0, s[22:23]
	global_load_dwordx4 v[152:155], v[2:3], off
	s_waitcnt vmcnt(7)
	ds_write_b128 v0, v[156:159] offset:40960
	v_lshl_add_u64 v[2:3], v[180:181], 0, s[22:23]
	global_load_dwordx4 v[156:159], v[2:3], off
	s_waitcnt vmcnt(7)
	ds_write_b128 v0, v[160:163] offset:16384
	v_lshl_add_u64 v[2:3], v[186:187], 0, s[22:23]
	global_load_dwordx4 v[160:163], v[2:3], off
	s_waitcnt vmcnt(7)
	ds_write_b128 v0, v[164:167] offset:49152
	v_lshl_add_u64 v[2:3], v[178:179], 0, s[22:23]
	global_load_dwordx4 v[164:167], v[2:3], off
	s_waitcnt vmcnt(7)
	ds_write_b128 v0, v[168:171] offset:24576
	v_lshl_add_u64 v[2:3], v[184:185], 0, s[22:23]
	global_load_dwordx4 v[168:171], v[2:3], off
	s_waitcnt vmcnt(7)
	ds_write_b128 v0, v[172:175] offset:57344
	v_lshl_add_u64 v[2:3], v[176:177], 0, s[22:23]
	global_load_dwordx4 v[172:175], v[2:3], off
	s_branch .Lfl_MLA_UP_0_done
.Lfl_MLA_UP_0_old:
	s_cmpk_eq_i32 s22, 0x780
	s_cbranch_scc1 .LBB0_717
	s_andn2_b32 s48, 0x10000, s26
	v_add_u32_e32 v0, s48, v201
	s_waitcnt vmcnt(7)
	ds_write_b128 v0, v[144:147]
	s_waitcnt vmcnt(6)
	ds_write_b128 v0, v[148:151] offset:32768
	s_waitcnt vmcnt(5)
	ds_write_b128 v0, v[152:155] offset:8192
	s_waitcnt vmcnt(4)
	ds_write_b128 v0, v[156:159] offset:40960
	s_waitcnt vmcnt(3)
	ds_write_b128 v0, v[160:163] offset:16384
	s_waitcnt vmcnt(2)
	ds_write_b128 v0, v[164:167] offset:49152
	s_waitcnt vmcnt(1)
	ds_write_b128 v0, v[168:171] offset:24576
	s_waitcnt vmcnt(0)
	ds_write_b128 v0, v[172:175] offset:57344

.Lfl_MLA_UP_0_done:
.LBB0_719:
	s_andn2_saveexec_b64 s[20:21], s[20:21]
	s_cbranch_execz .LBB0_721
	s_and_b32 s48, s26, 0x10000
	v_add_u32_e32 v0, s48, v195
	v_or_b32_e32 v2, s48, v196
	v_add_u32_e32 v14, v0, v197
	v_add_u32_e32 v15, v0, v198
	v_add_u32_e32 v208, v0, v199
	v_add_u32_e32 v0, v0, v200
	v_add_u32_e32 v209, v2, v197
	v_add_u32_e32 v210, v2, v198
	v_add_u32_e32 v211, v2, v199
	v_add_u32_e32 v214, v2, v200
	s_setprio 1
	ds_read_b128 v[2:5], v14 offset:0
	ds_read_b128 v[6:9], v14 offset:4096
	ds_read_b128 v[10:13], v14 offset:8192
	ds_read_b128 v[202:205], v14 offset:12288
	ds_read_b128 v[244:247], v209 offset:0
	ds_read_b128 v[248:251], v209 offset:4096
	ds_read_b128 v[228:231], v15 offset:0
	ds_read_b128 v[232:235], v15 offset:4096
	ds_read_b128 v[236:239], v15 offset:8192
	ds_read_b128 v[240:243], v15 offset:12288
	s_waitcnt lgkmcnt(4)
	v_mfma_f32_32x32x16_bf16 v[128:143], v[2:5], v[244:247], v[128:143]
	v_mfma_f32_32x32x16_bf16 v[96:111], v[6:9], v[244:247], v[96:111]
	v_mfma_f32_32x32x16_bf16 v[64:79], v[10:13], v[244:247], v[64:79]
	v_mfma_f32_32x32x16_bf16 v[32:47], v[202:205], v[244:247], v[32:47]
	ds_read_b128 v[244:247], v210 offset:0
	v_mfma_f32_32x32x16_bf16 v[112:127], v[2:5], v[248:251], v[112:127]
	v_mfma_f32_32x32x16_bf16 v[80:95], v[6:9], v[248:251], v[80:95]
	v_mfma_f32_32x32x16_bf16 v[48:63], v[10:13], v[248:251], v[48:63]
	v_mfma_f32_32x32x16_bf16 v[16:31], v[202:205], v[248:251], v[16:31]
	ds_read_b128 v[248:251], v210 offset:4096
	ds_read_b128 v[2:5], v208 offset:0
	ds_read_b128 v[6:9], v208 offset:4096
	ds_read_b128 v[10:13], v208 offset:8192
	ds_read_b128 v[202:205], v208 offset:12288
	s_waitcnt lgkmcnt(5)
	v_mfma_f32_32x32x16_bf16 v[128:143], v[228:231], v[244:247], v[128:143]
	v_mfma_f32_32x32x16_bf16 v[96:111], v[232:235], v[244:247], v[96:111]
	v_mfma_f32_32x32x16_bf16 v[64:79], v[236:239], v[244:247], v[64:79]
	v_mfma_f32_32x32x16_bf16 v[32:47], v[240:243], v[244:247], v[32:47]
	ds_read_b128 v[244:247], v211 offset:0
	s_waitcnt lgkmcnt(5)
	v_mfma_f32_32x32x16_bf16 v[112:127], v[228:231], v[248:251], v[112:127]
	v_mfma_f32_32x32x16_bf16 v[80:95], v[232:235], v[248:251], v[80:95]
	v_mfma_f32_32x32x16_bf16 v[48:63], v[236:239], v[248:251], v[48:63]
	v_mfma_f32_32x32x16_bf16 v[16:31], v[240:243], v[248:251], v[16:31]
	ds_read_b128 v[248:251], v211 offset:4096
	ds_read_b128 v[228:231], v0 offset:0
	ds_read_b128 v[232:235], v0 offset:4096
	ds_read_b128 v[236:239], v0 offset:8192
	ds_read_b128 v[240:243], v0 offset:12288
	s_waitcnt lgkmcnt(5)
	v_mfma_f32_32x32x16_bf16 v[128:143], v[2:5], v[244:247], v[128:143]
	v_mfma_f32_32x32x16_bf16 v[96:111], v[6:9], v[244:247], v[96:111]
	v_mfma_f32_32x32x16_bf16 v[64:79], v[10:13], v[244:247], v[64:79]
	v_mfma_f32_32x32x16_bf16 v[32:47], v[202:205], v[244:247], v[32:47]
	ds_read_b128 v[244:247], v214 offset:0
	s_waitcnt lgkmcnt(5)
	v_mfma_f32_32x32x16_bf16 v[112:127], v[2:5], v[248:251], v[112:127]
	v_mfma_f32_32x32x16_bf16 v[80:95], v[6:9], v[248:251], v[80:95]
	v_mfma_f32_32x32x16_bf16 v[48:63], v[10:13], v[248:251], v[48:63]
	v_mfma_f32_32x32x16_bf16 v[16:31], v[202:205], v[248:251], v[16:31]
	ds_read_b128 v[248:251], v214 offset:4096
	s_waitcnt lgkmcnt(1)
	v_mfma_f32_32x32x16_bf16 v[128:143], v[228:231], v[244:247], v[128:143]
	v_mfma_f32_32x32x16_bf16 v[96:111], v[232:235], v[244:247], v[96:111]
	v_mfma_f32_32x32x16_bf16 v[64:79], v[236:239], v[244:247], v[64:79]
	v_mfma_f32_32x32x16_bf16 v[32:47], v[240:243], v[244:247], v[32:47]
	s_waitcnt lgkmcnt(0)
	v_mfma_f32_32x32x16_bf16 v[112:127], v[228:231], v[248:251], v[112:127]
	v_mfma_f32_32x32x16_bf16 v[80:95], v[232:235], v[248:251], v[80:95]
	v_mfma_f32_32x32x16_bf16 v[48:63], v[236:239], v[248:251], v[48:63]
	v_mfma_f32_32x32x16_bf16 v[16:31], v[240:243], v[248:251], v[16:31]
	s_nop 15
	s_nop 7

	s_setprio 0
.LBB0_721:
	s_or_b64 exec, exec, s[20:21]
	s_and_saveexec_b64 s[20:21], s[44:45]
	s_xor_b64 s[20:21], exec, s[20:21]
	s_cbranch_execz .LBB0_726
	s_cmp_gt_u32 s27, 13
	s_cbranch_scc1 .Lfl_MLA_UP_1_old
	s_andn2_b32 s48, 0x10000, s26
	v_add_u32_e32 v0, s48, v201
	s_waitcnt vmcnt(7)
	ds_write_b128 v0, v[144:147]
	v_lshl_add_u64 v[2:3], v[190:191], 0, s[22:23]
	global_load_dwordx4 v[144:147], v[2:3], off
	s_waitcnt vmcnt(7)
	ds_write_b128 v0, v[148:151] offset:32768
	v_lshl_add_u64 v[2:3], v[182:183], 0, s[22:23]
	global_load_dwordx4 v[148:151], v[2:3], off
	s_waitcnt vmcnt(7)
	ds_write_b128 v0, v[152:155] offset:8192
	v_lshl_add_u64 v[2:3], v[188:189], 0, s[22:23]
	global_load_dwordx4 v[152:155], v[2:3], off
	s_waitcnt vmcnt(7)
	ds_write_b128 v0, v[156:159] offset:40960
	v_lshl_add_u64 v[2:3], v[180:181], 0, s[22:23]
	global_load_dwordx4 v[156:159], v[2:3], off
	s_waitcnt vmcnt(7)
	ds_write_b128 v0, v[160:163] offset:16384
	v_lshl_add_u64 v[2:3], v[186:187], 0, s[22:23]
	global_load_dwordx4 v[160:163], v[2:3], off
	s_waitcnt vmcnt(7)
	ds_write_b128 v0, v[164:167] offset:49152
	v_lshl_add_u64 v[2:3], v[178:179], 0, s[22:23]
	global_load_dwordx4 v[164:167], v[2:3], off
	s_waitcnt vmcnt(7)
	ds_write_b128 v0, v[168:171] offset:24576
	v_lshl_add_u64 v[2:3], v[184:185], 0, s[22:23]
	global_load_dwordx4 v[168:171], v[2:3], off
	s_waitcnt vmcnt(7)
	ds_write_b128 v0, v[172:175] offset:57344
	v_lshl_add_u64 v[2:3], v[176:177], 0, s[22:23]
	global_load_dwordx4 v[172:175], v[2:3], off
	s_branch .Lfl_MLA_UP_1_done

.Lfl_MLA_UP_1_done:
.LBB0_726:
	s_andn2_saveexec_b64 s[20:21], s[20:21]
	s_cbranch_execz .LBB0_713
	s_and_b32 s48, s26, 0x10000
	v_add_u32_e32 v0, s48, v195
	v_or_b32_e32 v2, s48, v196
	v_add_u32_e32 v14, v0, v197
	v_add_u32_e32 v15, v0, v198
	v_add_u32_e32 v208, v0, v199
	v_add_u32_e32 v0, v0, v200
	v_add_u32_e32 v209, v2, v197
	v_add_u32_e32 v210, v2, v198
	v_add_u32_e32 v211, v2, v199
	v_add_u32_e32 v214, v2, v200
	s_setprio 1
	ds_read_b128 v[2:5], v14 offset:0
	ds_read_b128 v[6:9], v14 offset:4096
	ds_read_b128 v[10:13], v14 offset:8192
	ds_read_b128 v[202:205], v14 offset:12288
	ds_read_b128 v[244:247], v209 offset:0
	ds_read_b128 v[248:251], v209 offset:4096
	ds_read_b128 v[228:231], v15 offset:0
	ds_read_b128 v[232:235], v15 offset:4096
	ds_read_b128 v[236:239], v15 offset:8192
	ds_read_b128 v[240:243], v15 offset:12288
	s_waitcnt lgkmcnt(4)
	v_mfma_f32_32x32x16_bf16 v[128:143], v[2:5], v[244:247], v[128:143]
	v_mfma_f32_32x32x16_bf16 v[96:111], v[6:9], v[244:247], v[96:111]
	v_mfma_f32_32x32x16_bf16 v[64:79], v[10:13], v[244:247], v[64:79]
	v_mfma_f32_32x32x16_bf16 v[32:47], v[202:205], v[244:247], v[32:47]
	ds_read_b128 v[244:247], v210 offset:0
	v_mfma_f32_32x32x16_bf16 v[112:127], v[2:5], v[248:251], v[112:127]
	v_mfma_f32_32x32x16_bf16 v[80:95], v[6:9], v[248:251], v[80:95]
	v_mfma_f32_32x32x16_bf16 v[48:63], v[10:13], v[248:251], v[48:63]
	v_mfma_f32_32x32x16_bf16 v[16:31], v[202:205], v[248:251], v[16:31]
	ds_read_b128 v[248:251], v210 offset:4096
	ds_read_b128 v[2:5], v208 offset:0
	ds_read_b128 v[6:9], v208 offset:4096
	ds_read_b128 v[10:13], v208 offset:8192
	ds_read_b128 v[202:205], v208 offset:12288
	s_waitcnt lgkmcnt(5)
	v_mfma_f32_32x32x16_bf16 v[128:143], v[228:231], v[244:247], v[128:143]
	v_mfma_f32_32x32x16_bf16 v[96:111], v[232:235], v[244:247], v[96:111]
	v_mfma_f32_32x32x16_bf16 v[64:79], v[236:239], v[244:247], v[64:79]
	v_mfma_f32_32x32x16_bf16 v[32:47], v[240:243], v[244:247], v[32:47]
	ds_read_b128 v[244:247], v211 offset:0
	s_waitcnt lgkmcnt(5)
	v_mfma_f32_32x32x16_bf16 v[112:127], v[228:231], v[248:251], v[112:127]
	v_mfma_f32_32x32x16_bf16 v[80:95], v[232:235], v[248:251], v[80:95]
	v_mfma_f32_32x32x16_bf16 v[48:63], v[236:239], v[248:251], v[48:63]
	v_mfma_f32_32x32x16_bf16 v[16:31], v[240:243], v[248:251], v[16:31]
	ds_read_b128 v[248:251], v211 offset:4096
	ds_read_b128 v[228:231], v0 offset:0
	ds_read_b128 v[232:235], v0 offset:4096
	ds_read_b128 v[236:239], v0 offset:8192
	ds_read_b128 v[240:243], v0 offset:12288
	s_waitcnt lgkmcnt(5)
	v_mfma_f32_32x32x16_bf16 v[128:143], v[2:5], v[244:247], v[128:143]
	v_mfma_f32_32x32x16_bf16 v[96:111], v[6:9], v[244:247], v[96:111]
	v_mfma_f32_32x32x16_bf16 v[64:79], v[10:13], v[244:247], v[64:79]
	v_mfma_f32_32x32x16_bf16 v[32:47], v[202:205], v[244:247], v[32:47]
	ds_read_b128 v[244:247], v214 offset:0
	s_waitcnt lgkmcnt(5)
	v_mfma_f32_32x32x16_bf16 v[112:127], v[2:5], v[248:251], v[112:127]
	v_mfma_f32_32x32x16_bf16 v[80:95], v[6:9], v[248:251], v[80:95]
	v_mfma_f32_32x32x16_bf16 v[48:63], v[10:13], v[248:251], v[48:63]
	v_mfma_f32_32x32x16_bf16 v[16:31], v[202:205], v[248:251], v[16:31]
	ds_read_b128 v[248:251], v214 offset:4096
	s_waitcnt lgkmcnt(1)
	v_mfma_f32_32x32x16_bf16 v[128:143], v[228:231], v[244:247], v[128:143]
	v_mfma_f32_32x32x16_bf16 v[96:111], v[232:235], v[244:247], v[96:111]
	v_mfma_f32_32x32x16_bf16 v[64:79], v[236:239], v[244:247], v[64:79]
	v_mfma_f32_32x32x16_bf16 v[32:47], v[240:243], v[244:247], v[32:47]
	s_waitcnt lgkmcnt(0)
	v_mfma_f32_32x32x16_bf16 v[112:127], v[228:231], v[248:251], v[112:127]
	v_mfma_f32_32x32x16_bf16 v[80:95], v[232:235], v[248:251], v[80:95]
	v_mfma_f32_32x32x16_bf16 v[48:63], v[236:239], v[248:251], v[48:63]
	v_mfma_f32_32x32x16_bf16 v[16:31], v[240:243], v[248:251], v[16:31]
	s_nop 15
	s_nop 7

	s_setprio 0
	s_branch .LBB0_713
